# ATTN: branch-merge and item-epilogue LDS chains pipelined (8 reads up front, counted waits, batched stores)
# speedup vs baseline: 1.0107x; 1.0107x over previous
.LBB0_1269:
	ds_bpermute_b32 v0, v155, v121
	ds_read_b128 v[236:239], v210
	ds_read_b128 v[240:243], v210 offset:1024
	ds_read_b128 v[244:247], v210 offset:2048
	ds_read_b128 v[248:251], v210 offset:3072
	ds_read_b128 v[134:137], v210 offset:4096
	ds_read_b128 v[138:141], v210 offset:5120
	ds_read_b128 v[142:145], v210 offset:6144
	ds_read_b128 v[146:149], v210 offset:7168
	v_mov_b32_e32 v123, v32
	v_mov_b32_e32 v125, v32
	v_mov_b32_e32 v127, v32
	v_mov_b32_e32 v129, v32
	s_waitcnt lgkmcnt(8)
	v_add_f32_e32 v0, v121, v0
	v_div_scale_f32 v1, s[0:1], v0, v0, v106
	v_rcp_f32_e32 v2, v1
	s_ashr_i32 s1, s39, 31
	s_add_u32 s0, s46, s39
	s_addc_u32 s1, s47, s1
	v_fma_f32 v3, -v1, v2, 1.0
	v_fmac_f32_e32 v2, v3, v2
	v_div_scale_f32 v3, vcc, v106, v0, v106
	v_mul_f32_e32 v4, v3, v2
	v_fma_f32 v5, -v1, v4, v3
	v_fmac_f32_e32 v4, v5, v2
	v_fma_f32 v1, -v1, v4, v3
	v_div_fmas_f32 v1, v1, v2, v4
	v_div_fixup_f32 v0, v1, v0, v106
	s_or_b64 s[0:1], s[0:1], s[60:61]
	s_lshl_b64 s[0:1], s[0:1], 11
	s_add_u32 s2, s26, s0
	s_addc_u32 s3, s27, s1
	s_lshl_b64 s[0:1], s[48:49], 1
	s_add_u32 s0, s2, s0
	s_addc_u32 s1, s3, s1
	v_mov_b32_e32 v121, v32
	s_add_i32 s38, s38, 1
	s_cmp_eq_u32 s38, s72
	s_waitcnt lgkmcnt(7)
	v_pk_fma_f32 v[236:237], v[64:65], v[0:1], v[236:237] op_sel_hi:[1,0,1]
	v_pk_fma_f32 v[238:239], v[66:67], v[0:1], v[238:239] op_sel_hi:[1,0,1]
	v_cvt_pk_bf16_f32 v2, v236, v237
	v_cvt_pk_bf16_f32 v3, v238, v239
	s_waitcnt lgkmcnt(6)
	v_pk_fma_f32 v[240:241], v[68:69], v[0:1], v[240:241] op_sel_hi:[1,0,1]
	v_pk_fma_f32 v[242:243], v[70:71], v[0:1], v[242:243] op_sel_hi:[1,0,1]
	v_cvt_pk_bf16_f32 v8, v240, v241
	v_cvt_pk_bf16_f32 v9, v242, v243
	s_waitcnt lgkmcnt(5)
	v_pk_fma_f32 v[244:245], v[72:73], v[0:1], v[244:245] op_sel_hi:[1,0,1]
	v_pk_fma_f32 v[246:247], v[74:75], v[0:1], v[246:247] op_sel_hi:[1,0,1]
	v_cvt_pk_bf16_f32 v10, v244, v245
	v_cvt_pk_bf16_f32 v11, v246, v247
	s_waitcnt lgkmcnt(4)
	v_pk_fma_f32 v[248:249], v[76:77], v[0:1], v[248:249] op_sel_hi:[1,0,1]
	v_pk_fma_f32 v[250:251], v[78:79], v[0:1], v[250:251] op_sel_hi:[1,0,1]
	v_cvt_pk_bf16_f32 v12, v248, v249
	v_cvt_pk_bf16_f32 v13, v250, v251
	s_waitcnt lgkmcnt(3)
	v_pk_fma_f32 v[134:135], v[48:49], v[0:1], v[134:135] op_sel_hi:[1,0,1]
	v_pk_fma_f32 v[136:137], v[50:51], v[0:1], v[136:137] op_sel_hi:[1,0,1]
	v_cvt_pk_bf16_f32 v14, v134, v135
	v_cvt_pk_bf16_f32 v15, v136, v137
	s_waitcnt lgkmcnt(2)
	v_pk_fma_f32 v[138:139], v[52:53], v[0:1], v[138:139] op_sel_hi:[1,0,1]
	v_pk_fma_f32 v[140:141], v[54:55], v[0:1], v[140:141] op_sel_hi:[1,0,1]
	v_cvt_pk_bf16_f32 v16, v138, v139
	v_cvt_pk_bf16_f32 v17, v140, v141
	s_waitcnt lgkmcnt(1)
	v_pk_fma_f32 v[142:143], v[56:57], v[0:1], v[142:143] op_sel_hi:[1,0,1]
	v_pk_fma_f32 v[144:145], v[58:59], v[0:1], v[144:145] op_sel_hi:[1,0,1]
	v_cvt_pk_bf16_f32 v18, v142, v143
	v_cvt_pk_bf16_f32 v19, v144, v145
	s_waitcnt lgkmcnt(0)
	v_pk_fma_f32 v[146:147], v[60:61], v[0:1], v[146:147] op_sel_hi:[1,0,1]
	v_pk_fma_f32 v[148:149], v[62:63], v[0:1], v[148:149] op_sel_hi:[1,0,1]
	s_nop 0
	v_cvt_pk_bf16_f32 v4, v146, v147
	v_cvt_pk_bf16_f32 v5, v148, v149
	ds_write2_b64 v206, v[2:3], v[8:9] offset1:2
	ds_write2_b64 v206, v[10:11], v[12:13] offset0:4 offset1:6
	ds_write2_b64 v206, v[14:15], v[16:17] offset0:8 offset1:10
	ds_write2_b64 v206, v[18:19], v[4:5] offset0:12 offset1:14
	s_waitcnt lgkmcnt(0)
	ds_read_b128 v[236:239], v207
	ds_read_b128 v[240:243], v208
	ds_read_b128 v[244:247], v208 offset:1152
	ds_read_b128 v[248:251], v208 offset:2304
	v_lshl_add_u64 v[4:5], s[0:1], 0, v[120:121]
	v_lshl_add_u64 v[6:7], v[4:5], 0, v[122:123]
	v_lshl_add_u64 v[8:9], v[4:5], 0, v[124:125]
	v_lshl_add_u64 v[10:11], v[4:5], 0, v[126:127]
	v_lshl_add_u64 v[4:5], v[4:5], 0, v[128:129]
	s_waitcnt lgkmcnt(3)
	global_store_dwordx4 v[6:7], v[236:239], off
	s_waitcnt lgkmcnt(2)
	global_store_dwordx4 v[8:9], v[240:243], off
	s_waitcnt lgkmcnt(1)
	global_store_dwordx4 v[10:11], v[244:247], off
	s_waitcnt lgkmcnt(0)
	global_store_dwordx4 v[4:5], v[248:251], off
	s_cbranch_scc1 .LBB0_1476

.LBB0_1453:
	s_cmp_lg_u32 s6, s2
	s_cbranch_scc1 .LBB0_1455
	ds_bpermute_b32 v0, v155, v121
	ds_read_b128 v[236:239], v210
	ds_read_b128 v[240:243], v210 offset:1024
	ds_read_b128 v[244:247], v210 offset:2048
	ds_read_b128 v[248:251], v210 offset:3072
	ds_read_b128 v[134:137], v210 offset:4096
	ds_read_b128 v[138:141], v210 offset:5120
	ds_read_b128 v[142:145], v210 offset:6144
	ds_read_b128 v[146:149], v210 offset:7168
	v_mov_b32_e32 v46, v32
	v_mov_b32_e32 v47, v32
	v_mov_b32_e32 v33, v32
	v_mov_b32_e32 v34, v32
	v_mov_b32_e32 v35, v32
	v_mov_b32_e32 v36, v32
	v_mov_b32_e32 v37, v32
	v_mov_b32_e32 v38, v32
	v_mov_b32_e32 v39, v32
	v_mov_b32_e32 v40, v32
	v_mov_b32_e32 v41, v32
	v_mov_b32_e32 v42, v32
	v_mov_b32_e32 v43, v32
	v_mov_b32_e32 v44, v32
	v_mov_b32_e32 v45, v32
	s_waitcnt lgkmcnt(8)
	v_add_f32_e32 v0, v121, v0
	v_div_scale_f32 v1, s[0:1], v0, v0, v105
	v_rcp_f32_e32 v2, v1
	s_nop 0
	v_fma_f32 v3, -v1, v2, 1.0
	v_fmac_f32_e32 v2, v3, v2
	v_div_scale_f32 v3, vcc, v105, v0, v105
	v_mul_f32_e32 v4, v3, v2
	v_fma_f32 v5, -v1, v4, v3
	v_fmac_f32_e32 v4, v5, v2
	v_fma_f32 v1, -v1, v4, v3
	v_div_fmas_f32 v1, v1, v2, v4
	v_div_fixup_f32 v0, v1, v0, v105
	v_mov_b32_e32 v121, 0
	v_mov_b32_e32 v123, 0xff800000
	s_waitcnt lgkmcnt(7)
	v_pk_fma_f32 v[236:237], v[64:65], v[0:1], v[236:237] op_sel_hi:[1,0,1]
	v_pk_fma_f32 v[238:239], v[66:67], v[0:1], v[238:239] op_sel_hi:[1,0,1]
	s_waitcnt lgkmcnt(6)
	v_pk_fma_f32 v[240:241], v[68:69], v[0:1], v[240:241] op_sel_hi:[1,0,1]
	v_pk_fma_f32 v[242:243], v[70:71], v[0:1], v[242:243] op_sel_hi:[1,0,1]
	s_waitcnt lgkmcnt(5)
	v_pk_fma_f32 v[244:245], v[72:73], v[0:1], v[244:245] op_sel_hi:[1,0,1]
	v_pk_fma_f32 v[246:247], v[74:75], v[0:1], v[246:247] op_sel_hi:[1,0,1]
	s_waitcnt lgkmcnt(4)
	v_pk_fma_f32 v[248:249], v[76:77], v[0:1], v[248:249] op_sel_hi:[1,0,1]
	v_pk_fma_f32 v[250:251], v[78:79], v[0:1], v[250:251] op_sel_hi:[1,0,1]
	s_waitcnt lgkmcnt(3)
	v_pk_fma_f32 v[134:135], v[48:49], v[0:1], v[134:135] op_sel_hi:[1,0,1]
	v_pk_fma_f32 v[136:137], v[50:51], v[0:1], v[136:137] op_sel_hi:[1,0,1]
	s_waitcnt lgkmcnt(2)
	v_pk_fma_f32 v[138:139], v[52:53], v[0:1], v[138:139] op_sel_hi:[1,0,1]
	v_pk_fma_f32 v[140:141], v[54:55], v[0:1], v[140:141] op_sel_hi:[1,0,1]
	s_waitcnt lgkmcnt(1)
	v_pk_fma_f32 v[142:143], v[56:57], v[0:1], v[142:143] op_sel_hi:[1,0,1]
	v_pk_fma_f32 v[144:145], v[58:59], v[0:1], v[144:145] op_sel_hi:[1,0,1]
	s_waitcnt lgkmcnt(0)
	v_pk_fma_f32 v[146:147], v[60:61], v[0:1], v[146:147] op_sel_hi:[1,0,1]
	v_pk_fma_f32 v[148:149], v[62:63], v[0:1], v[148:149] op_sel_hi:[1,0,1]
	ds_write_b128 v210, v[236:239]
	ds_write_b128 v210, v[240:243] offset:1024
	ds_write_b128 v210, v[244:247] offset:2048
	ds_write_b128 v210, v[248:251] offset:3072
	ds_write_b128 v210, v[134:137] offset:4096
	ds_write_b128 v210, v[138:141] offset:5120
	ds_write_b128 v210, v[142:145] offset:6144
	ds_write_b128 v210, v[146:149] offset:7168
	v_mov_b64_e32 v[78:79], v[46:47]
	v_mov_b64_e32 v[76:77], v[44:45]
	v_mov_b64_e32 v[74:75], v[42:43]
	v_mov_b64_e32 v[72:73], v[40:41]
	v_mov_b64_e32 v[70:71], v[38:39]
	v_mov_b64_e32 v[68:69], v[36:37]
	v_mov_b64_e32 v[66:67], v[34:35]
	v_mov_b64_e32 v[64:65], v[32:33]
	v_mov_b64_e32 v[62:63], v[46:47]
	v_mov_b64_e32 v[60:61], v[44:45]
	v_mov_b64_e32 v[58:59], v[42:43]
	v_mov_b64_e32 v[56:57], v[40:41]
	v_mov_b64_e32 v[54:55], v[38:39]
	v_mov_b64_e32 v[52:53], v[36:37]
	v_mov_b64_e32 v[50:51], v[34:35]
	v_mov_b64_e32 v[48:49], v[32:33]
